# GEMM1+GEMM2 ping-pong k-loops: the mid-k-step barrier (phase-alignment only; LDS hazards are covered by the closing barrier with the 4-stage ring) removed: one barrier per k-step
# baseline (speedup 1.0000x reference)
.LBB0_128:
	s_lshl_b32 s11, s7, 15
	v_or_b32_e32 v132, s11, v211
	v_add3_u32 v128, v132, s20, v212
	ds_read_b128 v[172:175], v128
	ds_read_b128 v[168:171], v128 offset:1024
	ds_read_b128 v[164:167], v128 offset:2048
	ds_read_b128 v[160:163], v128 offset:3072
	ds_read_b128 v[156:159], v128 offset:4096
	ds_read_b128 v[152:155], v128 offset:5120
	ds_read_b128 v[140:143], v128 offset:6144
	ds_read_b128 v[128:131], v128 offset:7168
	v_add3_u32 v132, v132, s40, v212
	ds_read_b128 v[148:151], v132 offset:16384
	ds_read_b128 v[144:147], v132 offset:17408
	ds_read_b128 v[136:139], v132 offset:18432
	ds_read_b128 v[132:135], v132 offset:19456
	s_cmp_lt_u32 s10, 29
	s_cselect_b64 s[0:1], -1, 0
	s_or_b64 s[12:13], s[8:9], s[0:1]
	s_cbranch_scc1 .Lgk_i1
	s_waitcnt vmcnt(0)
	s_branch .LBB0_127

.LBB0_138:
	s_waitcnt lgkmcnt(0)
	v_mfma_f32_16x16x32_bf16 v[124:127], v[144:147], v[172:175], v[124:127]
	s_waitcnt lgkmcnt(0)
	v_mfma_f32_16x16x32_bf16 v[120:123], v[148:151], v[172:175], v[120:123]
	v_mfma_f32_16x16x32_bf16 v[116:119], v[140:143], v[172:175], v[116:119]
	v_mfma_f32_16x16x32_bf16 v[112:115], v[132:135], v[172:175], v[112:115]
	v_mfma_f32_16x16x32_bf16 v[108:111], v[144:147], v[168:171], v[108:111]
	v_mfma_f32_16x16x32_bf16 v[104:107], v[148:151], v[168:171], v[104:107]
	v_mfma_f32_16x16x32_bf16 v[100:103], v[140:143], v[168:171], v[100:103]
	v_mfma_f32_16x16x32_bf16 v[96:99], v[132:135], v[168:171], v[96:99]
	v_mfma_f32_16x16x32_bf16 v[92:95], v[144:147], v[164:167], v[92:95]
	v_mfma_f32_16x16x32_bf16 v[88:91], v[148:151], v[164:167], v[88:91]
	v_mfma_f32_16x16x32_bf16 v[84:87], v[140:143], v[164:167], v[84:87]
	v_mfma_f32_16x16x32_bf16 v[80:83], v[132:135], v[164:167], v[80:83]
	v_mfma_f32_16x16x32_bf16 v[76:79], v[144:147], v[160:163], v[76:79]
	v_mfma_f32_16x16x32_bf16 v[72:75], v[148:151], v[160:163], v[72:75]
	v_mfma_f32_16x16x32_bf16 v[68:71], v[140:143], v[160:163], v[68:71]
	v_mfma_f32_16x16x32_bf16 v[64:67], v[132:135], v[160:163], v[64:67]
	v_mfma_f32_16x16x32_bf16 v[60:63], v[144:147], v[156:159], v[60:63]
	v_mfma_f32_16x16x32_bf16 v[56:59], v[148:151], v[156:159], v[56:59]
	v_mfma_f32_16x16x32_bf16 v[52:55], v[140:143], v[156:159], v[52:55]
	v_mfma_f32_16x16x32_bf16 v[48:51], v[132:135], v[156:159], v[48:51]
	v_mfma_f32_16x16x32_bf16 v[44:47], v[144:147], v[152:155], v[44:47]
	v_mfma_f32_16x16x32_bf16 v[40:43], v[148:151], v[152:155], v[40:43]
	v_mfma_f32_16x16x32_bf16 v[36:39], v[140:143], v[152:155], v[36:39]
	v_mfma_f32_16x16x32_bf16 v[32:35], v[132:135], v[152:155], v[32:35]
	v_mfma_f32_16x16x32_bf16 v[28:31], v[144:147], v[136:139], v[28:31]
	v_mfma_f32_16x16x32_bf16 v[24:27], v[148:151], v[136:139], v[24:27]
	v_mfma_f32_16x16x32_bf16 v[20:23], v[140:143], v[136:139], v[20:23]
	v_mfma_f32_16x16x32_bf16 v[16:19], v[132:135], v[136:139], v[16:19]
	v_mfma_f32_16x16x32_bf16 v[12:15], v[144:147], v[128:131], v[12:15]
	v_mfma_f32_16x16x32_bf16 v[8:11], v[148:151], v[128:131], v[8:11]
	v_mfma_f32_16x16x32_bf16 v[4:7], v[140:143], v[128:131], v[4:7]
	v_mfma_f32_16x16x32_bf16 v[0:3], v[132:135], v[128:131], v[0:3]
	s_cmp_lg_u64 s[12:13], 0
	s_cbranch_scc1 .Lgk_w1
	s_waitcnt vmcnt(8)
	s_branch .LBB0_135

.LBB0_702:
	s_lshl_b32 s54, s64, 15
	v_or_b32_e32 v132, s54, v202
	v_add3_u32 v128, v132, s33, v203
	ds_read_b128 v[172:175], v128
	ds_read_b128 v[168:171], v128 offset:1024
	ds_read_b128 v[164:167], v128 offset:2048
	ds_read_b128 v[160:163], v128 offset:3072
	ds_read_b128 v[156:159], v128 offset:4096
	ds_read_b128 v[152:155], v128 offset:5120
	ds_read_b128 v[140:143], v128 offset:6144
	ds_read_b128 v[128:131], v128 offset:7168
	v_add3_u32 v132, v132, s34, v203
	ds_read_b128 v[148:151], v132 offset:16384
	ds_read_b128 v[144:147], v132 offset:17408
	ds_read_b128 v[136:139], v132 offset:18432
	ds_read_b128 v[132:135], v132 offset:19456
	s_cmp_lt_u32 s39, 29
	s_cselect_b64 s[2:3], -1, 0
	s_or_b64 s[12:13], s[16:17], s[2:3]
	s_cbranch_scc1 .Lgk_i3
	s_waitcnt vmcnt(0)
	s_branch .LBB0_701

.LBB0_721:
	s_lshl_b32 s13, s64, 15
	v_or_b32_e32 v132, s13, v202
	v_add3_u32 v128, v132, s33, v203
	ds_read_b128 v[172:175], v128
	ds_read_b128 v[168:171], v128 offset:1024
	ds_read_b128 v[164:167], v128 offset:2048
	ds_read_b128 v[160:163], v128 offset:3072
	ds_read_b128 v[156:159], v128 offset:4096
	ds_read_b128 v[152:155], v128 offset:5120
	ds_read_b128 v[140:143], v128 offset:6144
	ds_read_b128 v[128:131], v128 offset:7168
	v_add3_u32 v132, v132, s34, v203
	ds_read_b128 v[148:151], v132 offset:16384
	ds_read_b128 v[144:147], v132 offset:17408
	ds_read_b128 v[136:139], v132 offset:18432
	ds_read_b128 v[132:135], v132 offset:19456
	s_cmp_lt_u32 s12, 29
	s_cselect_b64 s[0:1], -1, 0
	s_or_b64 s[8:9], s[16:17], s[0:1]
	s_cbranch_scc1 .Lgk_i4
	s_waitcnt vmcnt(0)
	s_branch .LBB0_720

.LBB0_731:
	s_waitcnt lgkmcnt(0)
	v_mfma_f32_16x16x32_bf16 v[124:127], v[172:175], v[144:147], v[124:127]
	s_waitcnt lgkmcnt(0)
	v_mfma_f32_16x16x32_bf16 v[120:123], v[172:175], v[148:151], v[120:123]
	v_mfma_f32_16x16x32_bf16 v[116:119], v[172:175], v[140:143], v[116:119]
	v_mfma_f32_16x16x32_bf16 v[112:115], v[172:175], v[132:135], v[112:115]
	v_mfma_f32_16x16x32_bf16 v[108:111], v[168:171], v[144:147], v[108:111]
	v_mfma_f32_16x16x32_bf16 v[104:107], v[168:171], v[148:151], v[104:107]
	v_mfma_f32_16x16x32_bf16 v[100:103], v[168:171], v[140:143], v[100:103]
	v_mfma_f32_16x16x32_bf16 v[96:99], v[168:171], v[132:135], v[96:99]
	v_mfma_f32_16x16x32_bf16 v[92:95], v[164:167], v[144:147], v[92:95]
	v_mfma_f32_16x16x32_bf16 v[88:91], v[164:167], v[148:151], v[88:91]
	v_mfma_f32_16x16x32_bf16 v[84:87], v[164:167], v[140:143], v[84:87]
	v_mfma_f32_16x16x32_bf16 v[80:83], v[164:167], v[132:135], v[80:83]
	v_mfma_f32_16x16x32_bf16 v[76:79], v[160:163], v[144:147], v[76:79]
	v_mfma_f32_16x16x32_bf16 v[72:75], v[160:163], v[148:151], v[72:75]
	v_mfma_f32_16x16x32_bf16 v[68:71], v[160:163], v[140:143], v[68:71]
	v_mfma_f32_16x16x32_bf16 v[64:67], v[160:163], v[132:135], v[64:67]
	v_mfma_f32_16x16x32_bf16 v[60:63], v[156:159], v[144:147], v[60:63]
	v_mfma_f32_16x16x32_bf16 v[56:59], v[156:159], v[148:151], v[56:59]
	v_mfma_f32_16x16x32_bf16 v[52:55], v[156:159], v[140:143], v[52:55]
	v_mfma_f32_16x16x32_bf16 v[48:51], v[156:159], v[132:135], v[48:51]
	v_mfma_f32_16x16x32_bf16 v[44:47], v[152:155], v[144:147], v[44:47]
	v_mfma_f32_16x16x32_bf16 v[40:43], v[152:155], v[148:151], v[40:43]
	v_mfma_f32_16x16x32_bf16 v[36:39], v[152:155], v[140:143], v[36:39]
	v_mfma_f32_16x16x32_bf16 v[32:35], v[152:155], v[132:135], v[32:35]
	v_mfma_f32_16x16x32_bf16 v[28:31], v[136:139], v[144:147], v[28:31]
	v_mfma_f32_16x16x32_bf16 v[24:27], v[136:139], v[148:151], v[24:27]
	v_mfma_f32_16x16x32_bf16 v[20:23], v[136:139], v[140:143], v[20:23]
	v_mfma_f32_16x16x32_bf16 v[16:19], v[136:139], v[132:135], v[16:19]
	v_mfma_f32_16x16x32_bf16 v[12:15], v[128:131], v[144:147], v[12:15]
	v_mfma_f32_16x16x32_bf16 v[8:11], v[128:131], v[148:151], v[8:11]
	v_mfma_f32_16x16x32_bf16 v[4:7], v[128:131], v[140:143], v[4:7]
	v_mfma_f32_16x16x32_bf16 v[0:3], v[128:131], v[132:135], v[0:3]
	s_cmp_lg_u64 s[8:9], 0
	s_cbranch_scc1 .Lgk_w4
	s_waitcnt vmcnt(8)
	s_branch .LBB0_728
